# attention phases: XCD-aware unit permutation (units sharing a kv head on one XCD)
# speedup vs baseline: 1.0117x; 1.0068x over previous
; __global__ void __launch_bounds__(512) mk_fwd(Params P) {
;     ...
;             for (int L = bid; L < nun; L += G) {
;                 int bq, hm, qb, seq, kvh;
;                 if (df) { if (L < 1024) { qb = (L & 15) + 1; hm = (L >> 4) & 15; bq = L >> 8; seq = TB; } else { const int L2 = L - 1024; hm = L2 & 15; bq = L2 >> 4; qb = 0; seq = CTXL; } kvh = hm >> 1; }
;                 else { qb = (L & 15) + 1; hm = (L >> 4) & 7; bq = L >> 7; seq = TB; kvh = hm >> 2; }
.LBB0_87:
	s_mov_b32 s15, s65
	s_cmp_lg_u32 s80, 0x100
	s_cbranch_scc1 .Latt_noperm
	s_cmpk_gt_i32 s65, 0x3ff
	s_cbranch_scc1 .Latt_noperm
	s_and_b32 s16, s65, 7
	s_lshl_b32 s16, s16, 5
	s_bfe_u32 s17, s65, 0x50003
	s_or_b32 s16, s16, s17
	s_andn2_b32 s15, s65, 0xff
	s_or_b32 s15, s15, s16
.Latt_noperm:
	s_mov_b64 s[8:9], -1
	s_and_b64 vcc, exec, s[54:55]
	s_cbranch_vccz .LBB0_89
	s_and_b32 s8, s15, 15
	s_add_i32 s12, s8, 1
	s_lshr_b32 s8, s15, 4
	s_bfe_u32 s11, s15, 0x30004
	s_ashr_i32 s10, s15, 7
	s_bfe_u32 s14, s8, 0x10002
	s_mov_b64 s[8:9], 0
.LBB0_89:
	s_andn2_b64 vcc, exec, s[8:9]
	s_movk_i32 s70, 0x44
	s_cbranch_vccnz .LBB0_96
	s_cmpk_gt_i32 s15, 0x3ff
	s_mov_b64 s[8:9], -1
	s_cbranch_scc0 .LBB0_92
	s_add_i32 s8, s15, 0xfffffc00
	s_lshr_b32 s10, s8, 4
	s_mov_b64 s[8:9], 0
.LBB0_92:
	s_andn2_b64 vcc, exec, s[8:9]
	s_cbranch_vccnz .LBB0_94
	s_and_b32 s8, s15, 15
	s_add_i32 s12, s8, 1
	s_lshr_b32 s8, s15, 4
	s_ashr_i32 s10, s15, 8
	s_branch .LBB0_95
.LBB0_94:
	s_mov_b32 s12, 0
	s_mov_b32 s70, 4
	s_mov_b32 s8, s15
